# in-proj epilogue: the write-once f32 K/V output stores carry the non-temporal hint so they do not displace re-read activations from the caches
# speedup vs baseline: 1.0092x; 1.0014x over previous
.LBB0_824:
	v_mul_f32_e64 v190, v226, -v228
	s_waitcnt vmcnt(0)
	v_pk_fma_f32 v[228:229], v[164:165], v[190:191], v[168:169] op_sel_hi:[1,0,1]
	v_pk_fma_f32 v[230:231], v[162:163], v[190:191], v[166:167] op_sel_hi:[1,0,1]
	v_pk_fma_f32 v[2:3], v[2:3], v[226:227], v[228:229] op_sel_hi:[1,0,1]
	v_pk_fma_f32 v[228:229], v[152:153], v[190:191], v[156:157] op_sel_hi:[1,0,1]
	v_pk_fma_f32 v[190:191], v[154:155], v[190:191], v[158:159] op_sel_hi:[1,0,1]
	v_pk_fma_f32 v[0:1], v[0:1], v[226:227], v[230:231] op_sel_hi:[1,0,1]
	v_pk_fma_f32 v[6:7], v[6:7], v[226:227], v[190:191] op_sel_hi:[1,0,1]
	v_mul_f32_e64 v190, v222, -v224
	v_pk_fma_f32 v[224:225], v[164:165], v[190:191], v[168:169] op_sel_hi:[1,0,1]
	v_pk_fma_f32 v[4:5], v[4:5], v[226:227], v[228:229] op_sel_hi:[1,0,1]
	v_pk_fma_f32 v[226:227], v[162:163], v[190:191], v[166:167] op_sel_hi:[1,0,1]
	v_pk_fma_f32 v[18:19], v[18:19], v[222:223], v[224:225] op_sel_hi:[1,0,1]
	v_pk_fma_f32 v[224:225], v[152:153], v[190:191], v[156:157] op_sel_hi:[1,0,1]
	v_pk_fma_f32 v[190:191], v[154:155], v[190:191], v[158:159] op_sel_hi:[1,0,1]
	v_pk_fma_f32 v[16:17], v[16:17], v[222:223], v[226:227] op_sel_hi:[1,0,1]
	v_pk_fma_f32 v[10:11], v[10:11], v[222:223], v[190:191] op_sel_hi:[1,0,1]
	v_mul_f32_e64 v190, v218, -v220
	v_pk_fma_f32 v[220:221], v[164:165], v[190:191], v[168:169] op_sel_hi:[1,0,1]
	v_pk_fma_f32 v[8:9], v[8:9], v[222:223], v[224:225] op_sel_hi:[1,0,1]
	v_pk_fma_f32 v[222:223], v[162:163], v[190:191], v[166:167] op_sel_hi:[1,0,1]
	v_pk_fma_f32 v[30:31], v[30:31], v[218:219], v[220:221] op_sel_hi:[1,0,1]
	v_pk_fma_f32 v[220:221], v[152:153], v[190:191], v[156:157] op_sel_hi:[1,0,1]
	v_pk_fma_f32 v[190:191], v[154:155], v[190:191], v[158:159] op_sel_hi:[1,0,1]
	v_pk_fma_f32 v[28:29], v[28:29], v[218:219], v[222:223] op_sel_hi:[1,0,1]
	v_pk_fma_f32 v[26:27], v[26:27], v[218:219], v[190:191] op_sel_hi:[1,0,1]
	v_mul_f32_e64 v190, v214, -v216
	v_pk_fma_f32 v[216:217], v[164:165], v[190:191], v[168:169] op_sel_hi:[1,0,1]
	v_pk_fma_f32 v[24:25], v[24:25], v[218:219], v[220:221] op_sel_hi:[1,0,1]
	v_pk_fma_f32 v[218:219], v[162:163], v[190:191], v[166:167] op_sel_hi:[1,0,1]
	v_pk_fma_f32 v[38:39], v[38:39], v[214:215], v[216:217] op_sel_hi:[1,0,1]
	v_pk_fma_f32 v[216:217], v[152:153], v[190:191], v[156:157] op_sel_hi:[1,0,1]
	v_pk_fma_f32 v[190:191], v[154:155], v[190:191], v[158:159] op_sel_hi:[1,0,1]
	v_pk_fma_f32 v[36:37], v[36:37], v[214:215], v[218:219] op_sel_hi:[1,0,1]
	v_pk_fma_f32 v[34:35], v[34:35], v[214:215], v[190:191] op_sel_hi:[1,0,1]
	v_mul_f32_e64 v190, v210, -v212
	v_pk_fma_f32 v[212:213], v[164:165], v[190:191], v[168:169] op_sel_hi:[1,0,1]
	v_pk_fma_f32 v[32:33], v[32:33], v[214:215], v[216:217] op_sel_hi:[1,0,1]
	v_pk_fma_f32 v[214:215], v[162:163], v[190:191], v[166:167] op_sel_hi:[1,0,1]
	v_pk_fma_f32 v[46:47], v[46:47], v[210:211], v[212:213] op_sel_hi:[1,0,1]
	v_pk_fma_f32 v[212:213], v[152:153], v[190:191], v[156:157] op_sel_hi:[1,0,1]
	v_pk_fma_f32 v[190:191], v[154:155], v[190:191], v[158:159] op_sel_hi:[1,0,1]
	v_pk_fma_f32 v[44:45], v[44:45], v[210:211], v[214:215] op_sel_hi:[1,0,1]
	v_pk_fma_f32 v[42:43], v[42:43], v[210:211], v[190:191] op_sel_hi:[1,0,1]
	v_mul_f32_e64 v190, v206, -v208
	v_pk_fma_f32 v[208:209], v[164:165], v[190:191], v[168:169] op_sel_hi:[1,0,1]
	v_pk_fma_f32 v[40:41], v[40:41], v[210:211], v[212:213] op_sel_hi:[1,0,1]
	v_pk_fma_f32 v[210:211], v[162:163], v[190:191], v[166:167] op_sel_hi:[1,0,1]
	v_pk_fma_f32 v[54:55], v[54:55], v[206:207], v[208:209] op_sel_hi:[1,0,1]
	v_pk_fma_f32 v[208:209], v[152:153], v[190:191], v[156:157] op_sel_hi:[1,0,1]
	v_pk_fma_f32 v[190:191], v[154:155], v[190:191], v[158:159] op_sel_hi:[1,0,1]
	v_pk_fma_f32 v[52:53], v[52:53], v[206:207], v[210:211] op_sel_hi:[1,0,1]
	v_pk_fma_f32 v[50:51], v[50:51], v[206:207], v[190:191] op_sel_hi:[1,0,1]
	v_mul_f32_e64 v190, v202, -v204
	v_pk_fma_f32 v[204:205], v[164:165], v[190:191], v[168:169] op_sel_hi:[1,0,1]
	v_pk_fma_f32 v[48:49], v[48:49], v[206:207], v[208:209] op_sel_hi:[1,0,1]
	v_pk_fma_f32 v[206:207], v[162:163], v[190:191], v[166:167] op_sel_hi:[1,0,1]
	v_pk_fma_f32 v[62:63], v[62:63], v[202:203], v[204:205] op_sel_hi:[1,0,1]
	v_pk_fma_f32 v[204:205], v[152:153], v[190:191], v[156:157] op_sel_hi:[1,0,1]
	v_pk_fma_f32 v[190:191], v[154:155], v[190:191], v[158:159] op_sel_hi:[1,0,1]
	v_pk_fma_f32 v[60:61], v[60:61], v[202:203], v[206:207] op_sel_hi:[1,0,1]
	v_pk_fma_f32 v[58:59], v[58:59], v[202:203], v[190:191] op_sel_hi:[1,0,1]
	v_mul_f32_e64 v190, v198, -v200
	v_pk_fma_f32 v[200:201], v[142:143], v[190:191], v[150:151] op_sel_hi:[1,0,1]
	v_pk_fma_f32 v[56:57], v[56:57], v[202:203], v[204:205] op_sel_hi:[1,0,1]
	v_pk_fma_f32 v[202:203], v[140:141], v[190:191], v[148:149] op_sel_hi:[1,0,1]
	v_pk_fma_f32 v[66:67], v[66:67], v[198:199], v[200:201] op_sel_hi:[1,0,1]
	v_pk_fma_f32 v[200:201], v[136:137], v[190:191], v[144:145] op_sel_hi:[1,0,1]
	v_pk_fma_f32 v[190:191], v[138:139], v[190:191], v[146:147] op_sel_hi:[1,0,1]
	v_pk_fma_f32 v[64:65], v[64:65], v[198:199], v[202:203] op_sel_hi:[1,0,1]
	v_pk_fma_f32 v[70:71], v[70:71], v[198:199], v[190:191] op_sel_hi:[1,0,1]
	v_mul_f32_e64 v190, v188, -v194
	v_pk_fma_f32 v[194:195], v[142:143], v[190:191], v[150:151] op_sel_hi:[1,0,1]
	v_pk_fma_f32 v[68:69], v[68:69], v[198:199], v[200:201] op_sel_hi:[1,0,1]
	v_pk_fma_f32 v[198:199], v[140:141], v[190:191], v[148:149] op_sel_hi:[1,0,1]
	v_pk_fma_f32 v[74:75], v[74:75], v[188:189], v[194:195] op_sel_hi:[1,0,1]
	v_pk_fma_f32 v[194:195], v[136:137], v[190:191], v[144:145] op_sel_hi:[1,0,1]
	v_pk_fma_f32 v[190:191], v[138:139], v[190:191], v[146:147] op_sel_hi:[1,0,1]
	v_mul_f32_e64 v184, v182, -v184
	v_pk_fma_f32 v[72:73], v[72:73], v[188:189], v[198:199] op_sel_hi:[1,0,1]
	v_pk_fma_f32 v[78:79], v[78:79], v[188:189], v[190:191] op_sel_hi:[1,0,1]
	v_pk_fma_f32 v[76:77], v[76:77], v[188:189], v[194:195] op_sel_hi:[1,0,1]
	v_pk_fma_f32 v[188:189], v[142:143], v[184:185], v[150:151] op_sel_hi:[1,0,1]
	v_pk_fma_f32 v[190:191], v[140:141], v[184:185], v[148:149] op_sel_hi:[1,0,1]
	v_pk_fma_f32 v[82:83], v[82:83], v[182:183], v[188:189] op_sel_hi:[1,0,1]
	v_pk_fma_f32 v[188:189], v[136:137], v[184:185], v[144:145] op_sel_hi:[1,0,1]
	v_pk_fma_f32 v[184:185], v[138:139], v[184:185], v[146:147] op_sel_hi:[1,0,1]
	v_mul_f32_e64 v180, v178, -v180
	v_pk_fma_f32 v[86:87], v[86:87], v[182:183], v[184:185] op_sel_hi:[1,0,1]
	v_pk_fma_f32 v[184:185], v[142:143], v[180:181], v[150:151] op_sel_hi:[1,0,1]
	v_pk_fma_f32 v[84:85], v[84:85], v[182:183], v[188:189] op_sel_hi:[1,0,1]
	v_pk_fma_f32 v[188:189], v[140:141], v[180:181], v[148:149] op_sel_hi:[1,0,1]
	v_pk_fma_f32 v[90:91], v[90:91], v[178:179], v[184:185] op_sel_hi:[1,0,1]
	v_pk_fma_f32 v[184:185], v[136:137], v[180:181], v[144:145] op_sel_hi:[1,0,1]
	v_pk_fma_f32 v[180:181], v[138:139], v[180:181], v[146:147] op_sel_hi:[1,0,1]
	v_mul_f32_e64 v176, v174, -v176
	v_pk_fma_f32 v[94:95], v[94:95], v[178:179], v[180:181] op_sel_hi:[1,0,1]
	v_pk_fma_f32 v[180:181], v[142:143], v[176:177], v[150:151] op_sel_hi:[1,0,1]
	v_pk_fma_f32 v[92:93], v[92:93], v[178:179], v[184:185] op_sel_hi:[1,0,1]
	v_pk_fma_f32 v[184:185], v[140:141], v[176:177], v[148:149] op_sel_hi:[1,0,1]
	v_pk_fma_f32 v[98:99], v[98:99], v[174:175], v[180:181] op_sel_hi:[1,0,1]
	v_pk_fma_f32 v[180:181], v[136:137], v[176:177], v[144:145] op_sel_hi:[1,0,1]
	v_pk_fma_f32 v[176:177], v[138:139], v[176:177], v[146:147] op_sel_hi:[1,0,1]
	v_mul_f32_e64 v126, v122, -v126
	v_pk_fma_f32 v[102:103], v[102:103], v[174:175], v[176:177] op_sel_hi:[1,0,1]
	v_pk_fma_f32 v[176:177], v[142:143], v[126:127], v[150:151] op_sel_hi:[1,0,1]
	v_pk_fma_f32 v[100:101], v[100:101], v[174:175], v[180:181] op_sel_hi:[1,0,1]
	v_pk_fma_f32 v[180:181], v[140:141], v[126:127], v[148:149] op_sel_hi:[1,0,1]
	v_pk_fma_f32 v[106:107], v[106:107], v[122:123], v[176:177] op_sel_hi:[1,0,1]
	v_pk_fma_f32 v[176:177], v[136:137], v[126:127], v[144:145] op_sel_hi:[1,0,1]
	v_pk_fma_f32 v[126:127], v[138:139], v[126:127], v[146:147] op_sel_hi:[1,0,1]
	v_pk_fma_f32 v[108:109], v[108:109], v[122:123], v[176:177] op_sel_hi:[1,0,1]
	v_pk_fma_f32 v[110:111], v[110:111], v[122:123], v[126:127] op_sel_hi:[1,0,1]
	v_mul_f32_e64 v126, v124, -v120
	v_pk_fma_f32 v[120:121], v[142:143], v[126:127], v[150:151] op_sel_hi:[1,0,1]
	v_pk_fma_f32 v[176:177], v[140:141], v[126:127], v[148:149] op_sel_hi:[1,0,1]
	v_pk_fma_f32 v[104:105], v[104:105], v[122:123], v[180:181] op_sel_hi:[1,0,1]
	v_pk_fma_f32 v[122:123], v[118:119], v[124:125], v[120:121] op_sel_hi:[1,0,1]
	v_pk_fma_f32 v[120:121], v[116:117], v[124:125], v[176:177] op_sel_hi:[1,0,1]
	v_pk_fma_f32 v[116:117], v[136:137], v[126:127], v[144:145] op_sel_hi:[1,0,1]
	v_pk_fma_f32 v[118:119], v[138:139], v[126:127], v[146:147] op_sel_hi:[1,0,1]
	s_lshl_b32 s4, s4, 8
	v_pk_fma_f32 v[126:127], v[114:115], v[124:125], v[118:119] op_sel_hi:[1,0,1]
	v_pk_fma_f32 v[124:125], v[112:113], v[124:125], v[116:117] op_sel_hi:[1,0,1]
	v_mul_f32_e64 v112, v160, -v172
	v_pk_fma_f32 v[116:117], v[140:141], v[112:113], v[148:149] op_sel_hi:[1,0,1]
	v_pk_fma_f32 v[114:115], v[142:143], v[112:113], v[150:151] op_sel_hi:[1,0,1]
	v_pk_fma_f32 v[140:141], v[20:21], v[160:161], v[116:117] op_sel_hi:[1,0,1]
	v_pk_fma_f32 v[20:21], v[136:137], v[112:113], v[144:145] op_sel_hi:[1,0,1]
	v_pk_fma_f32 v[142:143], v[22:23], v[160:161], v[114:115] op_sel_hi:[1,0,1]
	v_pk_fma_f32 v[22:23], v[138:139], v[112:113], v[146:147] op_sel_hi:[1,0,1]
	v_pk_fma_f32 v[136:137], v[12:13], v[160:161], v[20:21] op_sel_hi:[1,0,1]
	v_mul_f32_e64 v12, v186, -v196
	v_pk_fma_f32 v[138:139], v[14:15], v[160:161], v[22:23] op_sel_hi:[1,0,1]
	v_pk_fma_f32 v[14:15], v[164:165], v[12:13], v[168:169] op_sel_hi:[1,0,1]
	v_pk_fma_f32 v[20:21], v[162:163], v[12:13], v[166:167] op_sel_hi:[1,0,1]
	v_pk_fma_f32 v[112:113], v[152:153], v[12:13], v[156:157] op_sel_hi:[1,0,1]
	v_pk_fma_f32 v[12:13], v[154:155], v[12:13], v[158:159] op_sel_hi:[1,0,1]
	s_add_i32 s5, s5, s4
	v_pk_fma_f32 v[22:23], v[134:135], v[186:187], v[14:15] op_sel_hi:[1,0,1]
	v_pk_fma_f32 v[14:15], v[130:131], v[186:187], v[12:13] op_sel_hi:[1,0,1]
	v_pk_fma_f32 v[12:13], v[128:129], v[186:187], v[112:113] op_sel_hi:[1,0,1]
	v_or_b32_e32 v128, s5, v183
	s_ashr_i32 s4, s8, 1
	v_pk_fma_f32 v[80:81], v[80:81], v[182:183], v[190:191] op_sel_hi:[1,0,1]
	v_pk_fma_f32 v[88:89], v[88:89], v[178:179], v[188:189] op_sel_hi:[1,0,1]
	v_pk_fma_f32 v[96:97], v[96:97], v[174:175], v[184:185] op_sel_hi:[1,0,1]
	v_pk_fma_f32 v[20:21], v[132:133], v[186:187], v[20:21] op_sel_hi:[1,0,1]
	s_cmp_lg_u32 s4, 1
	v_ashrrev_i32_e32 v129, 31, v128
	s_cbranch_scc0 .LBB0_859
	s_cmp_gt_i32 s4, 4
	s_cselect_b64 s[8:9], -1, 0
	s_cmp_eq_u32 s4, 5
	s_cselect_b64 s[4:5], -1, 0
	s_and_b64 s[22:23], s[4:5], exec
	s_movk_i32 s19, 0xf600
	s_cselect_b32 s19, s19, 0xfffff400
	v_mov_b64_e32 v[114:115], s[0:1]
	v_add_u32_e32 v112, s19, v170
	v_mad_i64_i32 v[114:115], s[22:23], v128, s3, v[114:115]
	v_add_u32_e32 v160, 0xffff0000, v128
	v_lshl_add_u64 v[118:119], v[170:171], 1, v[114:115]
	v_cmp_gt_i32_e64 s[42:43], s2, v128
	v_lshlrev_b64 v[114:115], 11, v[160:161]
	v_lshlrev_b64 v[116:117], 11, v[128:129]
	v_cvt_pk_bf16_f32 v130, v140, v141
	v_cvt_pk_bf16_f32 v131, v142, v143
	v_cvt_pk_bf16_f32 v132, v136, v137
	v_cvt_pk_bf16_f32 v133, v138, v139
	s_and_b64 vcc, exec, s[8:9]
	v_ashrrev_i32_e32 v113, 31, v112
	global_store_dwordx4 v[118:119], v[130:133], off
	s_cbranch_vccz .LBB0_827
	s_and_b64 s[22:23], s[4:5], exec
	s_cselect_b32 s23, s51, s53
	s_cselect_b32 s22, s50, s52
	v_lshl_add_u64 v[130:131], s[22:23], 0, v[114:115]
	s_cselect_b32 s23, s59, s75
	s_cselect_b32 s22, s58, s74
	v_lshl_add_u64 v[132:133], s[22:23], 0, v[116:117]
	v_cndmask_b32_e64 v131, v131, v133, s[42:43]
	v_cndmask_b32_e64 v130, v130, v132, s[42:43]
	v_lshl_add_u64 v[130:131], v[112:113], 2, v[130:131]
	global_store_dwordx4 v[130:131], v[140:143], off nt
	global_store_dwordx4 v[130:131], v[136:139], off offset:16 nt
.LBB0_827:
	s_nop 0
	v_cvt_pk_bf16_f32 v130, v60, v61
	v_cvt_pk_bf16_f32 v131, v62, v63
	v_cvt_pk_bf16_f32 v132, v56, v57
	v_cvt_pk_bf16_f32 v133, v58, v59
	global_store_dwordx4 v[118:119], v[130:133], off offset:256
	v_cndmask_b32_e64 v118, 0, 1, s[8:9]
	v_cmp_ne_u32_e64 s[40:41], 1, v118
	s_andn2_b64 vcc, exec, s[8:9]
	s_cbranch_vccnz .LBB0_829
	s_and_b64 s[8:9], s[4:5], exec
	s_cselect_b32 s9, s59, s75
	s_cselect_b32 s8, s58, s74
	v_lshl_add_u64 v[116:117], s[8:9], 0, v[116:117]
	s_cselect_b32 s9, s51, s53
	s_cselect_b32 s8, s50, s52
	v_lshl_add_u64 v[114:115], s[8:9], 0, v[114:115]
	v_cndmask_b32_e64 v115, v115, v117, s[42:43]
	v_cndmask_b32_e64 v114, v114, v116, s[42:43]
	v_lshl_add_u64 v[114:115], v[112:113], 2, v[114:115]
	global_store_dwordx4 v[114:115], v[60:63], off offset:512 nt
	global_store_dwordx4 v[114:115], v[56:59], off offset:528 nt
.LBB0_829:
	v_or_b32_e32 v116, 16, v128
	v_mov_b64_e32 v[114:115], s[0:1]
	v_ashrrev_i32_e32 v117, 31, v116
	v_mad_i64_i32 v[114:115], s[8:9], v116, s3, v[114:115]
	v_add_u32_e32 v160, 0xffff0010, v128
	v_lshl_add_u64 v[118:119], v[170:171], 1, v[114:115]
	v_cmp_gt_i32_e64 s[42:43], s2, v116
	v_lshlrev_b64 v[114:115], 11, v[160:161]
	v_lshlrev_b64 v[116:117], 11, v[116:117]
	v_cvt_pk_bf16_f32 v130, v120, v121
	v_cvt_pk_bf16_f32 v131, v122, v123
	v_cvt_pk_bf16_f32 v132, v124, v125
	v_cvt_pk_bf16_f32 v133, v126, v127
	s_and_b64 vcc, exec, s[40:41]
	global_store_dwordx4 v[118:119], v[130:133], off
	s_cbranch_vccnz .LBB0_831
	s_and_b64 s[8:9], s[4:5], exec
	s_cselect_b32 s9, s59, s75
	s_cselect_b32 s8, s58, s74
	v_lshl_add_u64 v[130:131], s[8:9], 0, v[116:117]
	s_cselect_b32 s9, s51, s53
	s_cselect_b32 s8, s50, s52
	v_lshl_add_u64 v[132:133], s[8:9], 0, v[114:115]
	v_cndmask_b32_e64 v131, v133, v131, s[42:43]
	v_cndmask_b32_e64 v130, v132, v130, s[42:43]
	v_lshl_add_u64 v[130:131], v[112:113], 2, v[130:131]
	global_store_dwordx4 v[130:131], v[120:123], off nt
	global_store_dwordx4 v[130:131], v[124:127], off offset:16 nt
.LBB0_831:
	s_nop 0
	v_cvt_pk_bf16_f32 v130, v52, v53
	v_cvt_pk_bf16_f32 v131, v54, v55
	v_cvt_pk_bf16_f32 v132, v48, v49
	v_cvt_pk_bf16_f32 v133, v50, v51
	s_and_b64 vcc, exec, s[40:41]
	global_store_dwordx4 v[118:119], v[130:133], off offset:256
	s_cbranch_vccnz .LBB0_833
	s_and_b64 s[8:9], s[4:5], exec
	s_cselect_b32 s9, s59, s75
	s_cselect_b32 s8, s58, s74
	v_lshl_add_u64 v[116:117], s[8:9], 0, v[116:117]
	s_cselect_b32 s9, s51, s53
	s_cselect_b32 s8, s50, s52
	v_lshl_add_u64 v[114:115], s[8:9], 0, v[114:115]
	v_cndmask_b32_e64 v115, v115, v117, s[42:43]
	v_cndmask_b32_e64 v114, v114, v116, s[42:43]
	v_lshl_add_u64 v[114:115], v[112:113], 2, v[114:115]
	global_store_dwordx4 v[114:115], v[52:55], off offset:512 nt
	global_store_dwordx4 v[114:115], v[48:51], off offset:528 nt
.LBB0_833:
	v_or_b32_e32 v116, 32, v128
	v_mov_b64_e32 v[114:115], s[0:1]
	v_ashrrev_i32_e32 v117, 31, v116
	v_mad_i64_i32 v[114:115], s[8:9], v116, s3, v[114:115]
	v_add_u32_e32 v160, 0xffff0020, v128
	v_lshl_add_u64 v[118:119], v[170:171], 1, v[114:115]
	v_cmp_gt_i32_e64 s[42:43], s2, v116
	v_lshlrev_b64 v[114:115], 11, v[160:161]
	v_lshlrev_b64 v[116:117], 11, v[116:117]
	v_cvt_pk_bf16_f32 v130, v104, v105
	v_cvt_pk_bf16_f32 v131, v106, v107
	v_cvt_pk_bf16_f32 v132, v108, v109
	v_cvt_pk_bf16_f32 v133, v110, v111
	s_and_b64 vcc, exec, s[40:41]
	global_store_dwordx4 v[118:119], v[130:133], off
	s_cbranch_vccnz .LBB0_835
	s_and_b64 s[8:9], s[4:5], exec
	s_cselect_b32 s9, s59, s75
	s_cselect_b32 s8, s58, s74
	v_lshl_add_u64 v[130:131], s[8:9], 0, v[116:117]
	s_cselect_b32 s9, s51, s53
	s_cselect_b32 s8, s50, s52
	v_lshl_add_u64 v[132:133], s[8:9], 0, v[114:115]
	v_cndmask_b32_e64 v131, v133, v131, s[42:43]
	v_cndmask_b32_e64 v130, v132, v130, s[42:43]
	v_lshl_add_u64 v[130:131], v[112:113], 2, v[130:131]
	global_store_dwordx4 v[130:131], v[104:107], off nt
	global_store_dwordx4 v[130:131], v[108:111], off offset:16 nt
.LBB0_835:
	s_nop 0
	v_cvt_pk_bf16_f32 v130, v44, v45
	v_cvt_pk_bf16_f32 v131, v46, v47
	v_cvt_pk_bf16_f32 v132, v40, v41
	v_cvt_pk_bf16_f32 v133, v42, v43
	s_and_b64 vcc, exec, s[40:41]
	global_store_dwordx4 v[118:119], v[130:133], off offset:256
	s_cbranch_vccnz .LBB0_837
	s_and_b64 s[8:9], s[4:5], exec
	s_cselect_b32 s9, s59, s75
	s_cselect_b32 s8, s58, s74
	v_lshl_add_u64 v[116:117], s[8:9], 0, v[116:117]
	s_cselect_b32 s9, s51, s53
	s_cselect_b32 s8, s50, s52
	v_lshl_add_u64 v[114:115], s[8:9], 0, v[114:115]
	v_cndmask_b32_e64 v115, v115, v117, s[42:43]
	v_cndmask_b32_e64 v114, v114, v116, s[42:43]
	v_lshl_add_u64 v[114:115], v[112:113], 2, v[114:115]
	global_store_dwordx4 v[114:115], v[44:47], off offset:512 nt
	global_store_dwordx4 v[114:115], v[40:43], off offset:528 nt
.LBB0_837:
	v_or_b32_e32 v116, 48, v128
	v_mov_b64_e32 v[114:115], s[0:1]
	v_ashrrev_i32_e32 v117, 31, v116
	v_mad_i64_i32 v[114:115], s[8:9], v116, s3, v[114:115]
	v_add_u32_e32 v160, 0xffff0030, v128
	v_lshl_add_u64 v[118:119], v[170:171], 1, v[114:115]
	v_cmp_gt_i32_e64 s[42:43], s2, v116
	v_lshlrev_b64 v[114:115], 11, v[160:161]
	v_lshlrev_b64 v[116:117], 11, v[116:117]
	v_cvt_pk_bf16_f32 v130, v96, v97
	v_cvt_pk_bf16_f32 v131, v98, v99
	v_cvt_pk_bf16_f32 v132, v100, v101
	v_cvt_pk_bf16_f32 v133, v102, v103
	s_and_b64 vcc, exec, s[40:41]
	global_store_dwordx4 v[118:119], v[130:133], off
	s_cbranch_vccnz .LBB0_839
	s_and_b64 s[8:9], s[4:5], exec
	s_cselect_b32 s9, s59, s75
	s_cselect_b32 s8, s58, s74
	v_lshl_add_u64 v[130:131], s[8:9], 0, v[116:117]
	s_cselect_b32 s9, s51, s53
	s_cselect_b32 s8, s50, s52
	v_lshl_add_u64 v[132:133], s[8:9], 0, v[114:115]
	v_cndmask_b32_e64 v131, v133, v131, s[42:43]
	v_cndmask_b32_e64 v130, v132, v130, s[42:43]
	v_lshl_add_u64 v[130:131], v[112:113], 2, v[130:131]
	global_store_dwordx4 v[130:131], v[96:99], off nt
	global_store_dwordx4 v[130:131], v[100:103], off offset:16 nt
.LBB0_839:
	s_nop 0
	v_cvt_pk_bf16_f32 v130, v36, v37
	v_cvt_pk_bf16_f32 v131, v38, v39
	v_cvt_pk_bf16_f32 v132, v32, v33
	v_cvt_pk_bf16_f32 v133, v34, v35
	s_and_b64 vcc, exec, s[40:41]
	global_store_dwordx4 v[118:119], v[130:133], off offset:256
	s_cbranch_vccnz .LBB0_841
	s_and_b64 s[8:9], s[4:5], exec
	s_cselect_b32 s9, s59, s75
	s_cselect_b32 s8, s58, s74
	v_lshl_add_u64 v[116:117], s[8:9], 0, v[116:117]
	s_cselect_b32 s9, s51, s53
	s_cselect_b32 s8, s50, s52
	v_lshl_add_u64 v[114:115], s[8:9], 0, v[114:115]
	v_cndmask_b32_e64 v115, v115, v117, s[42:43]
	v_cndmask_b32_e64 v114, v114, v116, s[42:43]
	v_lshl_add_u64 v[114:115], v[112:113], 2, v[114:115]
	global_store_dwordx4 v[114:115], v[36:39], off offset:512 nt
	global_store_dwordx4 v[114:115], v[32:35], off offset:528 nt
.LBB0_841:
	v_add_u32_e32 v116, 0x80, v128
	v_mov_b64_e32 v[114:115], s[0:1]
	v_mad_i64_i32 v[114:115], s[8:9], v116, s3, v[114:115]
	v_ashrrev_i32_e32 v117, 31, v116
	s_mov_b32 s8, 0xff80
	v_add_u32_e32 v160, 0xffff0080, v128
	v_lshl_add_u64 v[118:119], v[170:171], 1, v[114:115]
	v_cmp_gt_i32_e64 s[42:43], s8, v128
	v_lshlrev_b64 v[114:115], 11, v[160:161]
	v_lshlrev_b64 v[116:117], 11, v[116:117]
	v_cvt_pk_bf16_f32 v130, v88, v89
	v_cvt_pk_bf16_f32 v131, v90, v91
	v_cvt_pk_bf16_f32 v132, v92, v93
	v_cvt_pk_bf16_f32 v133, v94, v95
	s_and_b64 vcc, exec, s[40:41]
	global_store_dwordx4 v[118:119], v[130:133], off
	s_cbranch_vccnz .LBB0_843
	s_and_b64 s[8:9], s[4:5], exec
	s_cselect_b32 s9, s59, s75
	s_cselect_b32 s8, s58, s74
	v_lshl_add_u64 v[130:131], s[8:9], 0, v[116:117]
	s_cselect_b32 s9, s51, s53
	s_cselect_b32 s8, s50, s52
	v_lshl_add_u64 v[132:133], s[8:9], 0, v[114:115]
	v_cndmask_b32_e64 v131, v133, v131, s[42:43]
	v_cndmask_b32_e64 v130, v132, v130, s[42:43]
	v_lshl_add_u64 v[130:131], v[112:113], 2, v[130:131]
	global_store_dwordx4 v[130:131], v[88:91], off nt
	global_store_dwordx4 v[130:131], v[92:95], off offset:16 nt
.LBB0_843:
	s_nop 0
	v_cvt_pk_bf16_f32 v130, v28, v29
	v_cvt_pk_bf16_f32 v131, v30, v31
	v_cvt_pk_bf16_f32 v132, v24, v25
	v_cvt_pk_bf16_f32 v133, v26, v27
	s_and_b64 vcc, exec, s[40:41]
	global_store_dwordx4 v[118:119], v[130:133], off offset:256
	s_cbranch_vccnz .LBB0_845
	s_and_b64 s[8:9], s[4:5], exec
	s_cselect_b32 s9, s59, s75
	s_cselect_b32 s8, s58, s74
	v_lshl_add_u64 v[116:117], s[8:9], 0, v[116:117]
	s_cselect_b32 s9, s51, s53
	s_cselect_b32 s8, s50, s52
	v_lshl_add_u64 v[114:115], s[8:9], 0, v[114:115]
	v_cndmask_b32_e64 v115, v115, v117, s[42:43]
	v_cndmask_b32_e64 v114, v114, v116, s[42:43]
	v_lshl_add_u64 v[114:115], v[112:113], 2, v[114:115]
	global_store_dwordx4 v[114:115], v[28:31], off offset:512 nt
	global_store_dwordx4 v[114:115], v[24:27], off offset:528 nt
.LBB0_845:
	v_add_u32_e32 v116, 0x90, v128
	v_mov_b64_e32 v[114:115], s[0:1]
	v_mad_i64_i32 v[114:115], s[8:9], v116, s3, v[114:115]
	v_ashrrev_i32_e32 v117, 31, v116
	s_mov_b32 s8, 0xff70
	v_add_u32_e32 v160, 0xffff0090, v128
	v_lshl_add_u64 v[118:119], v[170:171], 1, v[114:115]
	v_cmp_gt_i32_e64 s[42:43], s8, v128
	v_lshlrev_b64 v[114:115], 11, v[160:161]
	v_lshlrev_b64 v[116:117], 11, v[116:117]
	v_cvt_pk_bf16_f32 v130, v80, v81
	v_cvt_pk_bf16_f32 v131, v82, v83
	v_cvt_pk_bf16_f32 v132, v84, v85
	v_cvt_pk_bf16_f32 v133, v86, v87
	s_and_b64 vcc, exec, s[40:41]
	global_store_dwordx4 v[118:119], v[130:133], off
	s_cbranch_vccnz .LBB0_847
	s_and_b64 s[8:9], s[4:5], exec
	s_cselect_b32 s9, s59, s75
	s_cselect_b32 s8, s58, s74
	v_lshl_add_u64 v[130:131], s[8:9], 0, v[116:117]
	s_cselect_b32 s9, s51, s53
	s_cselect_b32 s8, s50, s52
	v_lshl_add_u64 v[132:133], s[8:9], 0, v[114:115]
	v_cndmask_b32_e64 v131, v133, v131, s[42:43]
	v_cndmask_b32_e64 v130, v132, v130, s[42:43]
	v_lshl_add_u64 v[130:131], v[112:113], 2, v[130:131]
	global_store_dwordx4 v[130:131], v[80:83], off nt
	global_store_dwordx4 v[130:131], v[84:87], off offset:16 nt
.LBB0_847:
	s_nop 0
	v_cvt_pk_bf16_f32 v130, v16, v17
	v_cvt_pk_bf16_f32 v131, v18, v19
	v_cvt_pk_bf16_f32 v132, v8, v9
	v_cvt_pk_bf16_f32 v133, v10, v11
	s_and_b64 vcc, exec, s[40:41]
	global_store_dwordx4 v[118:119], v[130:133], off offset:256
	s_cbranch_vccnz .LBB0_849
	s_and_b64 s[8:9], s[4:5], exec
	s_cselect_b32 s9, s59, s75
	s_cselect_b32 s8, s58, s74
	v_lshl_add_u64 v[116:117], s[8:9], 0, v[116:117]
	s_cselect_b32 s9, s51, s53
	s_cselect_b32 s8, s50, s52
	v_lshl_add_u64 v[114:115], s[8:9], 0, v[114:115]
	v_cndmask_b32_e64 v115, v115, v117, s[42:43]
	v_cndmask_b32_e64 v114, v114, v116, s[42:43]
	v_lshl_add_u64 v[114:115], v[112:113], 2, v[114:115]
	global_store_dwordx4 v[114:115], v[16:19], off offset:512 nt
	global_store_dwordx4 v[114:115], v[8:11], off offset:528 nt
.LBB0_849:
	v_add_u32_e32 v116, 0xa0, v128
	v_mov_b64_e32 v[114:115], s[0:1]
	v_mad_i64_i32 v[114:115], s[8:9], v116, s3, v[114:115]
	v_ashrrev_i32_e32 v117, 31, v116
	s_mov_b32 s8, 0xff60
	v_add_u32_e32 v160, 0xffff00a0, v128
	v_lshl_add_u64 v[118:119], v[170:171], 1, v[114:115]
	v_cmp_gt_i32_e64 s[42:43], s8, v128
	v_lshlrev_b64 v[114:115], 11, v[160:161]
	v_lshlrev_b64 v[116:117], 11, v[116:117]
	v_cvt_pk_bf16_f32 v130, v72, v73
	v_cvt_pk_bf16_f32 v131, v74, v75
	v_cvt_pk_bf16_f32 v132, v76, v77
	v_cvt_pk_bf16_f32 v133, v78, v79
	s_and_b64 vcc, exec, s[40:41]
	global_store_dwordx4 v[118:119], v[130:133], off
	s_cbranch_vccnz .LBB0_851
	s_and_b64 s[8:9], s[4:5], exec
	s_cselect_b32 s9, s59, s75
	s_cselect_b32 s8, s58, s74
	v_lshl_add_u64 v[130:131], s[8:9], 0, v[116:117]
	s_cselect_b32 s9, s51, s53
	s_cselect_b32 s8, s50, s52
	v_lshl_add_u64 v[132:133], s[8:9], 0, v[114:115]
	v_cndmask_b32_e64 v131, v133, v131, s[42:43]
	v_cndmask_b32_e64 v130, v132, v130, s[42:43]
	v_lshl_add_u64 v[130:131], v[112:113], 2, v[130:131]
	global_store_dwordx4 v[130:131], v[72:75], off nt
	global_store_dwordx4 v[130:131], v[76:79], off offset:16 nt
.LBB0_851:
	s_nop 0
	v_cvt_pk_bf16_f32 v130, v0, v1
	v_cvt_pk_bf16_f32 v131, v2, v3
	v_cvt_pk_bf16_f32 v132, v4, v5
	v_cvt_pk_bf16_f32 v133, v6, v7
	s_and_b64 vcc, exec, s[40:41]
	global_store_dwordx4 v[118:119], v[130:133], off offset:256
	s_cbranch_vccnz .LBB0_853
	s_and_b64 s[8:9], s[4:5], exec
	s_cselect_b32 s9, s59, s75
	s_cselect_b32 s8, s58, s74
	v_lshl_add_u64 v[116:117], s[8:9], 0, v[116:117]
	s_cselect_b32 s9, s51, s53
	s_cselect_b32 s8, s50, s52
	v_lshl_add_u64 v[114:115], s[8:9], 0, v[114:115]
	v_cndmask_b32_e64 v115, v115, v117, s[42:43]
	v_cndmask_b32_e64 v114, v114, v116, s[42:43]
	v_lshl_add_u64 v[114:115], v[112:113], 2, v[114:115]
	global_store_dwordx4 v[114:115], v[0:3], off offset:512 nt
	global_store_dwordx4 v[114:115], v[4:7], off offset:528 nt
.LBB0_853:
	v_add_u32_e32 v118, 0xb0, v128
	v_mov_b64_e32 v[114:115], s[0:1]
	v_mad_i64_i32 v[114:115], s[8:9], v118, s3, v[114:115]
	v_ashrrev_i32_e32 v119, 31, v118
	s_mov_b32 s8, 0xff50
	v_add_u32_e32 v160, 0xffff00b0, v128
	v_lshl_add_u64 v[116:117], v[170:171], 1, v[114:115]
	v_cmp_gt_i32_e64 s[42:43], s8, v128
	v_lshlrev_b64 v[114:115], 11, v[160:161]
	v_lshlrev_b64 v[118:119], 11, v[118:119]
	v_cvt_pk_bf16_f32 v130, v64, v65
	v_cvt_pk_bf16_f32 v131, v66, v67
	v_cvt_pk_bf16_f32 v132, v68, v69
	v_cvt_pk_bf16_f32 v133, v70, v71
	s_and_b64 vcc, exec, s[40:41]
	global_store_dwordx4 v[116:117], v[130:133], off
	s_cbranch_vccnz .LBB0_855
	s_and_b64 s[8:9], s[4:5], exec
	s_cselect_b32 s9, s59, s75
	s_cselect_b32 s8, s58, s74
	v_lshl_add_u64 v[130:131], s[8:9], 0, v[118:119]
	s_cselect_b32 s9, s51, s53
	s_cselect_b32 s8, s50, s52
	v_lshl_add_u64 v[132:133], s[8:9], 0, v[114:115]
	v_cndmask_b32_e64 v131, v133, v131, s[42:43]
	v_cndmask_b32_e64 v130, v132, v130, s[42:43]
	v_lshl_add_u64 v[130:131], v[112:113], 2, v[130:131]
	global_store_dwordx4 v[130:131], v[64:67], off nt
	global_store_dwordx4 v[130:131], v[68:71], off offset:16 nt
.LBB0_855:
	s_nop 0
	v_cvt_pk_bf16_f32 v130, v20, v21
	v_cvt_pk_bf16_f32 v131, v22, v23
	v_cvt_pk_bf16_f32 v132, v12, v13
	v_cvt_pk_bf16_f32 v133, v14, v15
	s_mov_b64 s[8:9], 0
	s_and_b64 vcc, exec, s[40:41]
	s_mov_b64 s[22:23], 0
	global_store_dwordx4 v[116:117], v[130:133], off offset:256
	s_cbranch_vccnz .LBB0_857
	s_and_b64 s[4:5], s[4:5], exec
	s_cselect_b32 s5, s59, s75
	s_cselect_b32 s4, s58, s74
	v_lshl_add_u64 v[116:117], s[4:5], 0, v[118:119]
	s_cselect_b32 s5, s51, s53
	s_cselect_b32 s4, s50, s52
	v_lshl_add_u64 v[114:115], s[4:5], 0, v[114:115]
	v_cndmask_b32_e64 v115, v115, v117, s[42:43]
	v_cndmask_b32_e64 v114, v114, v116, s[42:43]
	v_lshl_add_u64 v[112:113], v[112:113], 2, v[114:115]
	s_mov_b64 s[4:5], 0x200
	v_lshl_add_u64 v[116:117], v[112:113], 0, s[4:5]
	global_store_dwordx4 v[112:113], v[20:23], off offset:512 nt
	s_mov_b64 s[22:23], -1

.LBB0_861:
	global_store_dwordx4 v[116:117], v[12:15], off offset:16 nt
